# all validated micro-edits stacked on v7: cumsum and SGU load prefetch, SGU epilogue via LDS dwordx4, P4 epilogue load hoisting, DPP lane exchange in store epilogues, conflict-free K swizzle, static pr
# speedup vs baseline: 1.0101x; 1.0058x over previous
; __device__ __forceinline__ float bf2f(unsigned short h) { return __uint_as_float(((unsigned)h) << 16); }
; __device__ __forceinline__ unsigned cvtpk(float lo, float hi) { unsigned r; asm volatile("v_cvt_pk_bf16_f32 %0, %1, %2" : "=v"(r) : "v"(lo), "v"(hi)); return r; }
; __device__ __forceinline__ int crow(int r, int hi) { return (r & 3) + 8 * (r >> 2) + 4 * hi; }
; __device__ __forceinline__ void ph_misc(const Args& a, char* lds, int l) {
;     ...
;         for (int ci = 0; ci < 2; ++ci)
; #pragma unroll
;             for (int r = 0; r < 16; ++r) { const int t = 32 * tb + crow(r, hi), c = 32 * (cb0 + ci) + r32; const size_t row = row0 + t;
;                 const float uval = gelu_tanh(bf2f(P[row * NIN + PC_U + g * 128 + c])); const float val = uval * (acc[ci][r] + b_s[l * 512 + g * 128 + t]);
;                 const float vn = __shfl_xor(val, 1); if ((r32 & 1) == 0) *(unsigned*)(MIX + row * DM + 1024 + g * 128 + c) = cvtpk(val, vn); }
.LBB0_672:
	s_lshl_b64 s[0:1], s[34:35], 7
	v_or_b32_e32 v72, s0, v36
	v_mov_b64_e32 v[74:75], s[16:17]
	v_mad_u64_u32 v[74:75], s[6:7], v72, s83, v[74:75]
	v_mad_i32_i24 v75, s1, v244, v75
	s_lshl_b32 s86, s2, 1
	v_lshl_add_u64 v[74:75], v[74:75], 0, s[86:87]
	v_lshl_add_u64 v[74:75], v[38:39], 1, v[74:75]
	v_and_b32_e32 v200, 31, v243
	v_lshrrev_b32_e32 v201, 5, v243
	v_lshlrev_b32_e32 v202, 2, v201
	v_sub_u32_e32 v203, v36, v202
	v_add_u32_e32 v203, v203, v200
	v_or_b32_e32 v203, s0, v203
	v_mov_b64_e32 v[204:205], s[16:17]
	v_mad_u64_u32 v[204:205], s[6:7], v203, s83, v[204:205]
	v_mad_i32_i24 v205, s1, v244, v205
	v_lshl_add_u64 v[204:205], v[204:205], 0, s[86:87]
	v_lshl_add_u64 v[204:205], v[38:39], 1, v[204:205]
	v_lshlrev_b32_e32 v206, 6, v201
	v_add_co_u32_e32 v204, vcc, v204, v206
	s_nop 1
	v_addc_co_u32_e32 v205, vcc, 0, v205, vcc
	v_add_co_u32_e32 v204, vcc, 0x1000, v204
	s_nop 1
	v_addc_co_u32_e32 v205, vcc, 0, v205, vcc
	global_load_dword v207, v[204:205], off offset:512
	v_and_b32_e32 v208, 0xffffffc0, v240
	v_lshlrev_b32_e32 v208, 6, v208
	v_lshl_add_u32 v208, v201, 9, v208
	v_lshl_add_u32 v208, v200, 1, v208
	v_add_u32_e32 v208, 0xa000, v208
	s_movk_i32 s2, 0x1000
	v_add_co_u32_e32 v76, vcc, s2, v74
	v_or_b32_e32 v0, s38, v36
	s_nop 0
	v_addc_co_u32_e32 v77, vcc, 0, v75, vcc
	flat_load_ushort v61, v[76:77] offset:512
	v_lshl_add_u64 v[78:79], v[0:1], 2, s[14:15]
	flat_load_dword v0, v[78:79]
	v_mov_b32_e32 v73, s1
	v_lshlrev_b64 v[72:73], 12, v[72:73]
	v_lshl_add_u64 v[76:77], s[22:23], 0, v[72:73]
	s_waitcnt vmcnt(0) lgkmcnt(0)
	v_lshlrev_b32_e32 v61, 16, v61
	v_mul_f32_e32 v63, 0x3d372713, v61
	v_mul_f32_e32 v63, v63, v61
	v_fma_f32 v63, v63, v61, v61
	v_mul_f32_e32 v63, 0x3f4c422a, v63
	v_mul_f32_e32 v63, 0xc038aa3b, v63
	v_exp_f32_e32 v63, v63
	v_add_f32_e32 v0, v18, v0
	v_add_f32_e32 v63, 1.0, v63
	v_rcp_f32_e32 v63, v63
	s_nop 0
	v_mul_f32_e32 v61, v63, v61
	v_mul_f32_e32 v0, v0, v61
	s_nop 1
	v_mov_b32_dpp v18, v0 quad_perm:[1,0,3,2] row_mask:0xf bank_mask:0xf
	s_and_saveexec_b64 s[6:7], s[4:5]
	s_cbranch_execz .LBB0_674
	v_lshl_add_u64 v[72:73], v[76:77], 0, s[86:87]
	v_lshl_add_u64 v[72:73], v[38:39], 1, v[72:73]
	v_add_co_u32_e32 v72, vcc, 0x271c0000, v72
	s_waitcnt lgkmcnt(0)
	v_cvt_pk_bf16_f32 v0, v0, v18
	s_nop 0
	v_addc_co_u32_e32 v73, vcc, 0, v73, vcc
	ds_write_b32 v208, v0 offset:0
.LBB0_674:
	s_or_b64 exec, exec, s[6:7]
	s_waitcnt lgkmcnt(0)
	v_or_b32_e32 v18, s0, v40
	v_mov_b64_e32 v[72:73], s[16:17]
	v_mad_u64_u32 v[72:73], s[6:7], v18, s83, v[72:73]
	v_mad_i32_i24 v73, s1, v244, v73
	v_lshl_add_u64 v[72:73], v[72:73], 0, s[86:87]
	v_lshl_add_u64 v[80:81], v[38:39], 1, v[72:73]
	v_add_co_u32_e32 v72, vcc, s2, v80
	v_add_u32_e32 v0, s38, v36
	s_nop 0
	v_addc_co_u32_e32 v73, vcc, 0, v81, vcc
	flat_load_ushort v61, v[72:73] offset:512
	v_lshl_add_u64 v[72:73], v[0:1], 2, s[14:15]
	flat_load_dword v0, v[72:73] offset:4
	s_waitcnt vmcnt(0) lgkmcnt(0)
	v_lshlrev_b32_e32 v61, 16, v61
	v_mul_f32_e32 v63, 0x3d372713, v61
	v_mul_f32_e32 v63, v63, v61
	v_fma_f32 v63, v63, v61, v61
	v_mul_f32_e32 v63, 0x3f4c422a, v63
	v_mul_f32_e32 v63, 0xc038aa3b, v63
	v_exp_f32_e32 v63, v63
	v_add_f32_e32 v0, v19, v0
	v_mov_b32_e32 v19, s1
	v_lshlrev_b64 v[18:19], 12, v[18:19]
	v_add_f32_e32 v63, 1.0, v63
	v_rcp_f32_e32 v63, v63
	v_lshl_add_u64 v[18:19], s[22:23], 0, v[18:19]
	v_mul_f32_e32 v61, v63, v61
	v_mul_f32_e32 v0, v0, v61
	s_nop 1
	v_mov_b32_dpp v61, v0 quad_perm:[1,0,3,2] row_mask:0xf bank_mask:0xf
	s_and_saveexec_b64 s[6:7], s[4:5]
	s_cbranch_execz .LBB0_676
	v_lshl_add_u64 v[82:83], v[18:19], 0, s[86:87]
	v_lshl_add_u64 v[82:83], v[38:39], 1, v[82:83]
	v_add_co_u32_e32 v82, vcc, 0x271c0000, v82
	s_waitcnt lgkmcnt(0)
	v_cvt_pk_bf16_f32 v0, v0, v61
	s_nop 0
	v_addc_co_u32_e32 v83, vcc, 0, v83, vcc
	ds_write_b32 v208, v0 offset:128
.LBB0_676:
	s_or_b64 exec, exec, s[6:7]
	v_or_b32_e32 v84, s0, v42
	v_mov_b64_e32 v[82:83], s[16:17]
	v_mad_u64_u32 v[82:83], s[6:7], v84, s83, v[82:83]
	v_mad_i32_i24 v83, s1, v244, v83
	v_lshl_add_u64 v[82:83], v[82:83], 0, s[86:87]
	v_lshl_add_u64 v[82:83], v[38:39], 1, v[82:83]
	v_add_co_u32_e32 v86, vcc, s2, v82
	v_mov_b32_e32 v85, s1
	s_nop 0
	v_addc_co_u32_e32 v87, vcc, 0, v83, vcc
	flat_load_ushort v0, v[86:87] offset:512
	s_waitcnt lgkmcnt(0)
	flat_load_dword v61, v[72:73] offset:8
	v_lshlrev_b64 v[84:85], 12, v[84:85]
	v_lshl_add_u64 v[84:85], s[22:23], 0, v[84:85]
	s_waitcnt vmcnt(0)
	v_lshlrev_b32_e32 v0, 16, v0
	v_mul_f32_e32 v63, 0x3d372713, v0
	v_mul_f32_e32 v63, v63, v0
	v_fma_f32 v63, v63, v0, v0
	v_mul_f32_e32 v63, 0x3f4c422a, v63
	v_mul_f32_e32 v63, 0xc038aa3b, v63
	v_exp_f32_e32 v63, v63
	s_waitcnt lgkmcnt(0)
	v_add_f32_e32 v20, v20, v61
	v_add_f32_e32 v63, 1.0, v63
	v_rcp_f32_e32 v63, v63
	s_nop 0
	v_mul_f32_e32 v0, v63, v0
	v_mul_f32_e32 v0, v20, v0
	s_nop 1
	v_mov_b32_dpp v20, v0 quad_perm:[1,0,3,2] row_mask:0xf bank_mask:0xf
	s_and_saveexec_b64 s[6:7], s[4:5]
	s_cbranch_execz .LBB0_678
	v_lshl_add_u64 v[86:87], v[84:85], 0, s[86:87]
	v_lshl_add_u64 v[86:87], v[38:39], 1, v[86:87]
	v_add_co_u32_e32 v86, vcc, 0x271c0000, v86
	s_waitcnt lgkmcnt(0)
	v_cvt_pk_bf16_f32 v0, v0, v20
	s_nop 0
	v_addc_co_u32_e32 v87, vcc, 0, v87, vcc
	ds_write_b32 v208, v0 offset:256

; __device__ __forceinline__ float bf2f(unsigned short h) { return __uint_as_float(((unsigned)h) << 16); }
; __device__ __forceinline__ unsigned cvtpk(float lo, float hi) { unsigned r; asm volatile("v_cvt_pk_bf16_f32 %0, %1, %2" : "=v"(r) : "v"(lo), "v"(hi)); return r; }
; __device__ __forceinline__ int crow(int r, int hi) { return (r & 3) + 8 * (r >> 2) + 4 * hi; }
; __device__ __forceinline__ void ph_misc(const Args& a, char* lds, int l) {
;     ...
;         for (int ci = 0; ci < 2; ++ci)
; #pragma unroll
;             for (int r = 0; r < 16; ++r) { const int t = 32 * tb + crow(r, hi), c = 32 * (cb0 + ci) + r32; const size_t row = row0 + t;
;                 const float uval = gelu_tanh(bf2f(P[row * NIN + PC_U + g * 128 + c])); const float val = uval * (acc[ci][r] + b_s[l * 512 + g * 128 + t]);
;                 const float vn = __shfl_xor(val, 1); if ((r32 & 1) == 0) *(unsigned*)(MIX + row * DM + 1024 + g * 128 + c) = cvtpk(val, vn); }
.LBB0_680:
	s_or_b64 exec, exec, s[6:7]
	v_or_b32_e32 v90, s0, v46
	v_mov_b64_e32 v[88:89], s[16:17]
	v_mad_u64_u32 v[88:89], s[6:7], v90, s83, v[88:89]
	v_mad_i32_i24 v89, s1, v244, v89
	v_lshl_add_u64 v[88:89], v[88:89], 0, s[86:87]
	v_lshl_add_u64 v[88:89], v[38:39], 1, v[88:89]
	v_add_co_u32_e32 v92, vcc, s2, v88
	v_mov_b32_e32 v91, s1
	s_nop 0
	v_addc_co_u32_e32 v93, vcc, 0, v89, vcc
	flat_load_ushort v0, v[92:93] offset:512
	s_waitcnt lgkmcnt(0)
	flat_load_dword v61, v[72:73] offset:32
	v_lshlrev_b64 v[90:91], 12, v[90:91]
	v_lshl_add_u64 v[90:91], s[22:23], 0, v[90:91]
	s_waitcnt vmcnt(0)
	v_lshlrev_b32_e32 v0, 16, v0
	v_mul_f32_e32 v63, 0x3d372713, v0
	v_mul_f32_e32 v63, v63, v0
	v_fma_f32 v63, v63, v0, v0
	v_mul_f32_e32 v63, 0x3f4c422a, v63
	v_mul_f32_e32 v63, 0xc038aa3b, v63
	v_exp_f32_e32 v63, v63
	s_waitcnt lgkmcnt(0)
	v_add_f32_e32 v22, v22, v61
	v_add_f32_e32 v63, 1.0, v63
	v_rcp_f32_e32 v63, v63
	s_nop 0
	v_mul_f32_e32 v0, v63, v0
	v_mul_f32_e32 v0, v22, v0
	s_nop 1
	v_mov_b32_dpp v22, v0 quad_perm:[1,0,3,2] row_mask:0xf bank_mask:0xf
	s_and_saveexec_b64 s[6:7], s[4:5]
	s_cbranch_execz .LBB0_682
	v_lshl_add_u64 v[92:93], v[90:91], 0, s[86:87]
	v_lshl_add_u64 v[92:93], v[38:39], 1, v[92:93]
	v_add_co_u32_e32 v92, vcc, 0x271c0000, v92
	s_waitcnt lgkmcnt(0)
	v_cvt_pk_bf16_f32 v0, v0, v22
	s_nop 0
	v_addc_co_u32_e32 v93, vcc, 0, v93, vcc
	ds_write_b32 v208, v0 offset:1024

; __device__ __forceinline__ float bf2f(unsigned short h) { return __uint_as_float(((unsigned)h) << 16); }
; __device__ __forceinline__ unsigned cvtpk(float lo, float hi) { unsigned r; asm volatile("v_cvt_pk_bf16_f32 %0, %1, %2" : "=v"(r) : "v"(lo), "v"(hi)); return r; }
; __device__ __forceinline__ int crow(int r, int hi) { return (r & 3) + 8 * (r >> 2) + 4 * hi; }
; __device__ __forceinline__ void ph_misc(const Args& a, char* lds, int l) {
;     ...
;         for (int ci = 0; ci < 2; ++ci)
; #pragma unroll
;             for (int r = 0; r < 16; ++r) { const int t = 32 * tb + crow(r, hi), c = 32 * (cb0 + ci) + r32; const size_t row = row0 + t;
;                 const float uval = gelu_tanh(bf2f(P[row * NIN + PC_U + g * 128 + c])); const float val = uval * (acc[ci][r] + b_s[l * 512 + g * 128 + t]);
;                 const float vn = __shfl_xor(val, 1); if ((r32 & 1) == 0) *(unsigned*)(MIX + row * DM + 1024 + g * 128 + c) = cvtpk(val, vn); }
.LBB0_684:
	s_or_b64 exec, exec, s[6:7]
	v_or_b32_e32 v96, s0, v50
	v_mov_b64_e32 v[94:95], s[16:17]
	v_mad_u64_u32 v[94:95], s[6:7], v96, s83, v[94:95]
	v_mad_i32_i24 v95, s1, v244, v95
	v_lshl_add_u64 v[94:95], v[94:95], 0, s[86:87]
	v_lshl_add_u64 v[94:95], v[38:39], 1, v[94:95]
	v_add_co_u32_e32 v98, vcc, s2, v94
	v_mov_b32_e32 v97, s1
	s_nop 0
	v_addc_co_u32_e32 v99, vcc, 0, v95, vcc
	flat_load_ushort v0, v[98:99] offset:512
	s_waitcnt lgkmcnt(0)
	flat_load_dword v61, v[72:73] offset:40
	v_lshlrev_b64 v[96:97], 12, v[96:97]
	v_lshl_add_u64 v[96:97], s[22:23], 0, v[96:97]
	s_waitcnt vmcnt(0)
	v_lshlrev_b32_e32 v0, 16, v0
	v_mul_f32_e32 v63, 0x3d372713, v0
	v_mul_f32_e32 v63, v63, v0
	v_fma_f32 v63, v63, v0, v0
	v_mul_f32_e32 v63, 0x3f4c422a, v63
	v_mul_f32_e32 v63, 0xc038aa3b, v63
	v_exp_f32_e32 v63, v63
	s_waitcnt lgkmcnt(0)
	v_add_f32_e32 v24, v24, v61
	v_add_f32_e32 v63, 1.0, v63
	v_rcp_f32_e32 v63, v63
	s_nop 0
	v_mul_f32_e32 v0, v63, v0
	v_mul_f32_e32 v0, v24, v0
	s_nop 1
	v_mov_b32_dpp v24, v0 quad_perm:[1,0,3,2] row_mask:0xf bank_mask:0xf
	s_and_saveexec_b64 s[6:7], s[4:5]
	s_cbranch_execz .LBB0_686
	v_lshl_add_u64 v[98:99], v[96:97], 0, s[86:87]
	v_lshl_add_u64 v[98:99], v[38:39], 1, v[98:99]
	v_add_co_u32_e32 v98, vcc, 0x271c0000, v98
	s_waitcnt lgkmcnt(0)
	v_cvt_pk_bf16_f32 v0, v0, v24
	s_nop 0
	v_addc_co_u32_e32 v99, vcc, 0, v99, vcc
	ds_write_b32 v208, v0 offset:1280

; __device__ __forceinline__ float bf2f(unsigned short h) { return __uint_as_float(((unsigned)h) << 16); }
; __device__ __forceinline__ unsigned cvtpk(float lo, float hi) { unsigned r; asm volatile("v_cvt_pk_bf16_f32 %0, %1, %2" : "=v"(r) : "v"(lo), "v"(hi)); return r; }
; __device__ __forceinline__ int crow(int r, int hi) { return (r & 3) + 8 * (r >> 2) + 4 * hi; }
; __device__ __forceinline__ void ph_misc(const Args& a, char* lds, int l) {
;     ...
;         for (int ci = 0; ci < 2; ++ci)
; #pragma unroll
;             for (int r = 0; r < 16; ++r) { const int t = 32 * tb + crow(r, hi), c = 32 * (cb0 + ci) + r32; const size_t row = row0 + t;
;                 const float uval = gelu_tanh(bf2f(P[row * NIN + PC_U + g * 128 + c])); const float val = uval * (acc[ci][r] + b_s[l * 512 + g * 128 + t]);
;                 const float vn = __shfl_xor(val, 1); if ((r32 & 1) == 0) *(unsigned*)(MIX + row * DM + 1024 + g * 128 + c) = cvtpk(val, vn); }
.LBB0_688:
	s_or_b64 exec, exec, s[6:7]
	v_or_b32_e32 v102, s0, v54
	v_mov_b64_e32 v[100:101], s[16:17]
	v_mad_u64_u32 v[100:101], s[6:7], v102, s83, v[100:101]
	v_mad_i32_i24 v101, s1, v244, v101
	v_lshl_add_u64 v[100:101], v[100:101], 0, s[86:87]
	v_lshl_add_u64 v[100:101], v[38:39], 1, v[100:101]
	v_add_co_u32_e32 v104, vcc, s2, v100
	v_mov_b32_e32 v103, s1
	s_nop 0
	v_addc_co_u32_e32 v105, vcc, 0, v101, vcc
	flat_load_ushort v0, v[104:105] offset:512
	s_waitcnt lgkmcnt(0)
	flat_load_dword v61, v[72:73] offset:64
	v_lshlrev_b64 v[102:103], 12, v[102:103]
	v_lshl_add_u64 v[102:103], s[22:23], 0, v[102:103]
	s_waitcnt vmcnt(0)
	v_lshlrev_b32_e32 v0, 16, v0
	v_mul_f32_e32 v63, 0x3d372713, v0
	v_mul_f32_e32 v63, v63, v0
	v_fma_f32 v63, v63, v0, v0
	v_mul_f32_e32 v63, 0x3f4c422a, v63
	v_mul_f32_e32 v63, 0xc038aa3b, v63
	v_exp_f32_e32 v63, v63
	s_waitcnt lgkmcnt(0)
	v_add_f32_e32 v26, v26, v61
	v_add_f32_e32 v63, 1.0, v63
	v_rcp_f32_e32 v63, v63
	s_nop 0
	v_mul_f32_e32 v0, v63, v0
	v_mul_f32_e32 v0, v26, v0
	s_nop 1
	v_mov_b32_dpp v26, v0 quad_perm:[1,0,3,2] row_mask:0xf bank_mask:0xf
	s_and_saveexec_b64 s[6:7], s[4:5]
	s_cbranch_execz .LBB0_690
	v_lshl_add_u64 v[104:105], v[102:103], 0, s[86:87]
	v_lshl_add_u64 v[104:105], v[38:39], 1, v[104:105]
	v_add_co_u32_e32 v104, vcc, 0x271c0000, v104
	s_waitcnt lgkmcnt(0)
	v_cvt_pk_bf16_f32 v0, v0, v26
	s_nop 0
	v_addc_co_u32_e32 v105, vcc, 0, v105, vcc
	ds_write_b32 v208, v0 offset:2048

; __device__ __forceinline__ float bf2f(unsigned short h) { return __uint_as_float(((unsigned)h) << 16); }
; __device__ __forceinline__ unsigned cvtpk(float lo, float hi) { unsigned r; asm volatile("v_cvt_pk_bf16_f32 %0, %1, %2" : "=v"(r) : "v"(lo), "v"(hi)); return r; }
; __device__ __forceinline__ int crow(int r, int hi) { return (r & 3) + 8 * (r >> 2) + 4 * hi; }
; __device__ __forceinline__ void ph_misc(const Args& a, char* lds, int l) {
;     ...
;         for (int ci = 0; ci < 2; ++ci)
; #pragma unroll
;             for (int r = 0; r < 16; ++r) { const int t = 32 * tb + crow(r, hi), c = 32 * (cb0 + ci) + r32; const size_t row = row0 + t;
;                 const float uval = gelu_tanh(bf2f(P[row * NIN + PC_U + g * 128 + c])); const float val = uval * (acc[ci][r] + b_s[l * 512 + g * 128 + t]);
;                 const float vn = __shfl_xor(val, 1); if ((r32 & 1) == 0) *(unsigned*)(MIX + row * DM + 1024 + g * 128 + c) = cvtpk(val, vn); }
.LBB0_692:
	s_or_b64 exec, exec, s[6:7]
	v_or_b32_e32 v108, s0, v58
	v_mov_b64_e32 v[106:107], s[16:17]
	v_mad_u64_u32 v[106:107], s[6:7], v108, s83, v[106:107]
	v_mad_i32_i24 v107, s1, v244, v107
	v_lshl_add_u64 v[106:107], v[106:107], 0, s[86:87]
	v_lshl_add_u64 v[106:107], v[38:39], 1, v[106:107]
	v_add_co_u32_e32 v110, vcc, s2, v106
	v_mov_b32_e32 v109, s1
	s_nop 0
	v_addc_co_u32_e32 v111, vcc, 0, v107, vcc
	flat_load_ushort v0, v[110:111] offset:512
	s_waitcnt lgkmcnt(0)
	flat_load_dword v61, v[72:73] offset:72
	v_lshlrev_b64 v[108:109], 12, v[108:109]
	v_lshl_add_u64 v[108:109], s[22:23], 0, v[108:109]
	s_waitcnt vmcnt(0)
	v_lshlrev_b32_e32 v0, 16, v0
	v_mul_f32_e32 v63, 0x3d372713, v0
	v_mul_f32_e32 v63, v63, v0
	v_fma_f32 v63, v63, v0, v0
	v_mul_f32_e32 v63, 0x3f4c422a, v63
	v_mul_f32_e32 v63, 0xc038aa3b, v63
	v_exp_f32_e32 v63, v63
	s_waitcnt lgkmcnt(0)
	v_add_f32_e32 v28, v28, v61
	v_add_f32_e32 v63, 1.0, v63
	v_rcp_f32_e32 v63, v63
	s_nop 0
	v_mul_f32_e32 v0, v63, v0
	v_mul_f32_e32 v0, v28, v0
	s_nop 1
	v_mov_b32_dpp v28, v0 quad_perm:[1,0,3,2] row_mask:0xf bank_mask:0xf
	s_and_saveexec_b64 s[6:7], s[4:5]
	s_cbranch_execz .LBB0_694
	v_lshl_add_u64 v[110:111], v[108:109], 0, s[86:87]
	v_lshl_add_u64 v[110:111], v[38:39], 1, v[110:111]
	v_add_co_u32_e32 v110, vcc, 0x271c0000, v110
	s_waitcnt lgkmcnt(0)
	v_cvt_pk_bf16_f32 v0, v0, v28
	s_nop 0
	v_addc_co_u32_e32 v111, vcc, 0, v111, vcc
	ds_write_b32 v208, v0 offset:2304

; __device__ __forceinline__ float bf2f(unsigned short h) { return __uint_as_float(((unsigned)h) << 16); }
; __device__ __forceinline__ unsigned cvtpk(float lo, float hi) { unsigned r; asm volatile("v_cvt_pk_bf16_f32 %0, %1, %2" : "=v"(r) : "v"(lo), "v"(hi)); return r; }
; __device__ __forceinline__ int crow(int r, int hi) { return (r & 3) + 8 * (r >> 2) + 4 * hi; }
; __device__ __forceinline__ void ph_misc(const Args& a, char* lds, int l) {
;     ...
;         for (int ci = 0; ci < 2; ++ci)
; #pragma unroll
;             for (int r = 0; r < 16; ++r) { const int t = 32 * tb + crow(r, hi), c = 32 * (cb0 + ci) + r32; const size_t row = row0 + t;
;                 const float uval = gelu_tanh(bf2f(P[row * NIN + PC_U + g * 128 + c])); const float val = uval * (acc[ci][r] + b_s[l * 512 + g * 128 + t]);
;                 const float vn = __shfl_xor(val, 1); if ((r32 & 1) == 0) *(unsigned*)(MIX + row * DM + 1024 + g * 128 + c) = cvtpk(val, vn); }
.LBB0_696:
	s_or_b64 exec, exec, s[6:7]
	v_or_b32_e32 v114, s0, v62
	v_mov_b64_e32 v[112:113], s[16:17]
	v_mad_u64_u32 v[112:113], s[6:7], v114, s83, v[112:113]
	v_mad_i32_i24 v113, s1, v244, v113
	v_lshl_add_u64 v[112:113], v[112:113], 0, s[86:87]
	v_lshl_add_u64 v[112:113], v[38:39], 1, v[112:113]
	v_add_co_u32_e32 v116, vcc, s2, v112
	v_mov_b32_e32 v115, s1
	s_nop 0
	v_addc_co_u32_e32 v117, vcc, 0, v113, vcc
	flat_load_ushort v0, v[116:117] offset:512
	s_waitcnt lgkmcnt(0)
	flat_load_dword v61, v[72:73] offset:96
	v_lshlrev_b64 v[114:115], 12, v[114:115]
	v_lshl_add_u64 v[114:115], s[22:23], 0, v[114:115]
	s_waitcnt vmcnt(0)
	v_lshlrev_b32_e32 v0, 16, v0
	v_mul_f32_e32 v63, 0x3d372713, v0
	v_mul_f32_e32 v63, v63, v0
	v_fma_f32 v63, v63, v0, v0
	v_mul_f32_e32 v63, 0x3f4c422a, v63
	v_mul_f32_e32 v63, 0xc038aa3b, v63
	v_exp_f32_e32 v63, v63
	s_waitcnt lgkmcnt(0)
	v_add_f32_e32 v30, v30, v61
	v_add_f32_e32 v63, 1.0, v63
	v_rcp_f32_e32 v63, v63
	s_nop 0
	v_mul_f32_e32 v0, v63, v0
	v_mul_f32_e32 v0, v30, v0
	s_nop 1
	v_mov_b32_dpp v30, v0 quad_perm:[1,0,3,2] row_mask:0xf bank_mask:0xf
	s_and_saveexec_b64 s[6:7], s[4:5]
	s_cbranch_execz .LBB0_698
	v_lshl_add_u64 v[116:117], v[114:115], 0, s[86:87]
	v_lshl_add_u64 v[116:117], v[38:39], 1, v[116:117]
	v_add_co_u32_e32 v116, vcc, 0x271c0000, v116
	s_waitcnt lgkmcnt(0)
	v_cvt_pk_bf16_f32 v0, v0, v30
	s_nop 0
	v_addc_co_u32_e32 v117, vcc, 0, v117, vcc
	ds_write_b32 v208, v0 offset:3072

; __device__ __forceinline__ float bf2f(unsigned short h) { return __uint_as_float(((unsigned)h) << 16); }
; __device__ __forceinline__ unsigned cvtpk(float lo, float hi) { unsigned r; asm volatile("v_cvt_pk_bf16_f32 %0, %1, %2" : "=v"(r) : "v"(lo), "v"(hi)); return r; }
; __device__ __forceinline__ int crow(int r, int hi) { return (r & 3) + 8 * (r >> 2) + 4 * hi; }
; __device__ __forceinline__ void ph_misc(const Args& a, char* lds, int l) {
;     ...
;         for (int ci = 0; ci < 2; ++ci)
; #pragma unroll
;             for (int r = 0; r < 16; ++r) { const int t = 32 * tb + crow(r, hi), c = 32 * (cb0 + ci) + r32; const size_t row = row0 + t;
;                 const float uval = gelu_tanh(bf2f(P[row * NIN + PC_U + g * 128 + c])); const float val = uval * (acc[ci][r] + b_s[l * 512 + g * 128 + t]);
;                 const float vn = __shfl_xor(val, 1); if ((r32 & 1) == 0) *(unsigned*)(MIX + row * DM + 1024 + g * 128 + c) = cvtpk(val, vn); }
.LBB0_700:
	s_or_b64 exec, exec, s[6:7]
	v_or_b32_e32 v120, s0, v66
	v_mov_b64_e32 v[118:119], s[16:17]
	v_mad_u64_u32 v[118:119], s[6:7], v120, s83, v[118:119]
	v_mad_i32_i24 v119, s1, v244, v119
	v_lshl_add_u64 v[118:119], v[118:119], 0, s[86:87]
	v_lshl_add_u64 v[118:119], v[38:39], 1, v[118:119]
	v_add_co_u32_e32 v122, vcc, s2, v118
	v_mov_b32_e32 v121, s1
	s_nop 0
	v_addc_co_u32_e32 v123, vcc, 0, v119, vcc
	flat_load_ushort v0, v[122:123] offset:512
	s_waitcnt lgkmcnt(0)
	flat_load_dword v61, v[72:73] offset:104
	v_lshlrev_b64 v[120:121], 12, v[120:121]
	v_lshl_add_u64 v[120:121], s[22:23], 0, v[120:121]
	s_waitcnt vmcnt(0)
	v_lshlrev_b32_e32 v0, 16, v0
	v_mul_f32_e32 v63, 0x3d372713, v0
	v_mul_f32_e32 v63, v63, v0
	v_fma_f32 v63, v63, v0, v0
	v_mul_f32_e32 v63, 0x3f4c422a, v63
	v_mul_f32_e32 v63, 0xc038aa3b, v63
	v_exp_f32_e32 v63, v63
	s_waitcnt lgkmcnt(0)
	v_add_f32_e32 v32, v32, v61
	v_add_f32_e32 v63, 1.0, v63
	v_rcp_f32_e32 v63, v63
	s_nop 0
	v_mul_f32_e32 v0, v63, v0
	v_mul_f32_e32 v0, v32, v0
	s_nop 1
	v_mov_b32_dpp v32, v0 quad_perm:[1,0,3,2] row_mask:0xf bank_mask:0xf
	s_and_saveexec_b64 s[6:7], s[4:5]
	s_cbranch_execz .LBB0_702
	v_lshl_add_u64 v[122:123], v[120:121], 0, s[86:87]
	v_lshl_add_u64 v[122:123], v[38:39], 1, v[122:123]
	v_add_co_u32_e32 v122, vcc, 0x271c0000, v122
	s_waitcnt lgkmcnt(0)
	v_cvt_pk_bf16_f32 v0, v0, v32
	s_nop 0
	v_addc_co_u32_e32 v123, vcc, 0, v123, vcc
	ds_write_b32 v208, v0 offset:3328

; __device__ __forceinline__ float bf2f(unsigned short h) { return __uint_as_float(((unsigned)h) << 16); }
; __device__ __forceinline__ unsigned cvtpk(float lo, float hi) { unsigned r; asm volatile("v_cvt_pk_bf16_f32 %0, %1, %2" : "=v"(r) : "v"(lo), "v"(hi)); return r; }
; __device__ __forceinline__ int crow(int r, int hi) { return (r & 3) + 8 * (r >> 2) + 4 * hi; }
; __device__ __forceinline__ void ph_misc(const Args& a, char* lds, int l) {
;     ...
;         for (int ci = 0; ci < 2; ++ci)
; #pragma unroll
;             for (int r = 0; r < 16; ++r) { const int t = 32 * tb + crow(r, hi), c = 32 * (cb0 + ci) + r32; const size_t row = row0 + t;
;                 const float uval = gelu_tanh(bf2f(P[row * NIN + PC_U + g * 128 + c])); const float val = uval * (acc[ci][r] + b_s[l * 512 + g * 128 + t]);
;                 const float vn = __shfl_xor(val, 1); if ((r32 & 1) == 0) *(unsigned*)(MIX + row * DM + 1024 + g * 128 + c) = cvtpk(val, vn); }
.LBB0_704:
	s_or_b64 exec, exec, s[0:1]
	s_mov_b64 s[0:1], 0x1200
	v_lshl_add_u64 v[74:75], v[74:75], 0, s[0:1]
	flat_load_ushort v0, v[74:75] offset:64
	s_waitcnt lgkmcnt(0)
	flat_load_dword v61, v[78:79]
	s_waitcnt vmcnt(0)
	v_lshlrev_b32_e32 v0, 16, v0
	v_mul_f32_e32 v63, 0x3d372713, v0
	v_mul_f32_e32 v63, v63, v0
	v_fma_f32 v63, v63, v0, v0
	v_mul_f32_e32 v63, 0x3f4c422a, v63
	v_mul_f32_e32 v63, 0xc038aa3b, v63
	v_exp_f32_e32 v63, v63
	s_waitcnt lgkmcnt(0)
	v_add_f32_e32 v2, v2, v61
	v_add_f32_e32 v63, 1.0, v63
	v_rcp_f32_e32 v63, v63
	s_nop 0
	v_mul_f32_e32 v0, v63, v0
	v_mul_f32_e32 v0, v2, v0
	s_nop 1
	v_mov_b32_dpp v2, v0 quad_perm:[1,0,3,2] row_mask:0xf bank_mask:0xf
	s_and_saveexec_b64 s[0:1], s[4:5]
	s_cbranch_execz .LBB0_706
	v_lshl_add_u64 v[74:75], v[76:77], 0, s[86:87]
	v_lshl_add_u64 v[74:75], v[38:39], 1, v[74:75]
	v_add_co_u32_e32 v74, vcc, 0x271c0000, v74
	s_waitcnt lgkmcnt(0)
	v_cvt_pk_bf16_f32 v0, v0, v2
	s_nop 0
	v_addc_co_u32_e32 v75, vcc, 0, v75, vcc
	ds_write_b32 v208, v0 offset:64
.LBB0_706:
	s_or_b64 exec, exec, s[0:1]
	s_mov_b64 s[0:1], 0x1200
	v_lshl_add_u64 v[74:75], v[80:81], 0, s[0:1]
	flat_load_ushort v0, v[74:75] offset:64
	s_waitcnt lgkmcnt(0)
	flat_load_dword v2, v[72:73] offset:4
	s_waitcnt vmcnt(0)
	v_lshlrev_b32_e32 v0, 16, v0
	v_mul_f32_e32 v61, 0x3d372713, v0
	v_mul_f32_e32 v61, v61, v0
	v_fma_f32 v61, v61, v0, v0
	v_mul_f32_e32 v61, 0x3f4c422a, v61
	v_mul_f32_e32 v61, 0xc038aa3b, v61
	v_exp_f32_e32 v61, v61
	s_waitcnt lgkmcnt(0)
	v_add_f32_e32 v2, v3, v2
	v_add_f32_e32 v61, 1.0, v61
	v_rcp_f32_e32 v61, v61
	s_nop 0
	v_mul_f32_e32 v0, v61, v0
	v_mul_f32_e32 v0, v2, v0
	s_nop 1
	v_mov_b32_dpp v2, v0 quad_perm:[1,0,3,2] row_mask:0xf bank_mask:0xf
	s_and_saveexec_b64 s[0:1], s[4:5]
	s_cbranch_execz .LBB0_708
	v_lshl_add_u64 v[18:19], v[18:19], 0, s[86:87]
	v_lshl_add_u64 v[18:19], v[38:39], 1, v[18:19]
	s_waitcnt lgkmcnt(0)
	v_cvt_pk_bf16_f32 v0, v0, v2
	v_add_co_u32_e32 v2, vcc, 0x271c0000, v18
	s_nop 1
	v_addc_co_u32_e32 v3, vcc, 0, v19, vcc
	ds_write_b32 v208, v0 offset:192
.LBB0_708:
	s_or_b64 exec, exec, s[0:1]
	s_mov_b64 s[0:1], 0x1200
	s_waitcnt lgkmcnt(0)
	v_lshl_add_u64 v[2:3], v[82:83], 0, s[0:1]
	flat_load_ushort v0, v[2:3] offset:64
	s_nop 0
	flat_load_dword v2, v[72:73] offset:8
	s_waitcnt vmcnt(0) lgkmcnt(0)
	v_lshlrev_b32_e32 v0, 16, v0
	v_mul_f32_e32 v3, 0x3d372713, v0
	v_mul_f32_e32 v3, v3, v0
	v_fma_f32 v3, v3, v0, v0
	v_mul_f32_e32 v3, 0x3f4c422a, v3
	v_mul_f32_e32 v3, 0xc038aa3b, v3
	v_exp_f32_e32 v3, v3
	v_add_f32_e32 v2, v4, v2
	v_add_f32_e32 v3, 1.0, v3
	v_rcp_f32_e32 v3, v3
	s_nop 0
	v_mul_f32_e32 v0, v3, v0
	v_mul_f32_e32 v0, v2, v0
	s_nop 1
	v_mov_b32_dpp v2, v0 quad_perm:[1,0,3,2] row_mask:0xf bank_mask:0xf
	s_and_saveexec_b64 s[0:1], s[4:5]
	s_cbranch_execz .LBB0_710
	v_lshl_add_u64 v[18:19], v[84:85], 0, s[86:87]
	v_lshl_add_u64 v[18:19], v[38:39], 1, v[18:19]
	s_waitcnt lgkmcnt(0)
	v_cvt_pk_bf16_f32 v0, v0, v2
	v_add_co_u32_e32 v2, vcc, 0x271c0000, v18
	s_nop 1
	v_addc_co_u32_e32 v3, vcc, 0, v19, vcc
	ds_write_b32 v208, v0 offset:320
.LBB0_710:
	s_or_b64 exec, exec, s[0:1]
	s_mov_b64 s[0:1], 0x1200
	s_waitcnt lgkmcnt(0)
	v_lshl_add_u64 v[2:3], v[86:87], 0, s[0:1]
	flat_load_ushort v0, v[2:3] offset:64
	s_nop 0
	flat_load_dword v2, v[72:73] offset:12
	s_waitcnt vmcnt(0) lgkmcnt(0)
	v_lshlrev_b32_e32 v0, 16, v0
	v_mul_f32_e32 v3, 0x3d372713, v0
	v_mul_f32_e32 v3, v3, v0
	v_fma_f32 v3, v3, v0, v0
	v_mul_f32_e32 v3, 0x3f4c422a, v3
	v_mul_f32_e32 v3, 0xc038aa3b, v3
	v_exp_f32_e32 v3, v3
	v_add_f32_e32 v2, v5, v2
	v_add_f32_e32 v3, 1.0, v3
	v_rcp_f32_e32 v3, v3
	s_nop 0
	v_mul_f32_e32 v0, v3, v0
	v_mul_f32_e32 v0, v2, v0
	s_nop 1
	v_mov_b32_dpp v2, v0 quad_perm:[1,0,3,2] row_mask:0xf bank_mask:0xf
	s_and_saveexec_b64 s[0:1], s[4:5]
	s_cbranch_execz .LBB0_712
	v_lshl_add_u64 v[4:5], v[20:21], 0, s[86:87]
	v_lshl_add_u64 v[4:5], v[38:39], 1, v[4:5]
	s_waitcnt lgkmcnt(0)
	v_cvt_pk_bf16_f32 v0, v0, v2
	v_add_co_u32_e32 v2, vcc, 0x271c0000, v4
	s_nop 1
	v_addc_co_u32_e32 v3, vcc, 0, v5, vcc
	ds_write_b32 v208, v0 offset:448
.LBB0_712:
	s_or_b64 exec, exec, s[0:1]
	s_mov_b64 s[0:1], 0x1200
	s_waitcnt lgkmcnt(0)
	v_lshl_add_u64 v[2:3], v[88:89], 0, s[0:1]
	flat_load_ushort v0, v[2:3] offset:64
	s_nop 0
	flat_load_dword v2, v[72:73] offset:32
	s_waitcnt vmcnt(0) lgkmcnt(0)
	v_lshlrev_b32_e32 v0, 16, v0
	v_mul_f32_e32 v3, 0x3d372713, v0
	v_mul_f32_e32 v3, v3, v0
	v_fma_f32 v3, v3, v0, v0
	v_mul_f32_e32 v3, 0x3f4c422a, v3
	v_mul_f32_e32 v3, 0xc038aa3b, v3
	v_exp_f32_e32 v3, v3
	v_add_f32_e32 v2, v6, v2
	v_add_f32_e32 v3, 1.0, v3
	v_rcp_f32_e32 v3, v3
	s_nop 0
	v_mul_f32_e32 v0, v3, v0
	v_mul_f32_e32 v0, v2, v0
	s_nop 1
	v_mov_b32_dpp v2, v0 quad_perm:[1,0,3,2] row_mask:0xf bank_mask:0xf
	s_and_saveexec_b64 s[0:1], s[4:5]
	s_cbranch_execz .LBB0_714
	v_lshl_add_u64 v[4:5], v[90:91], 0, s[86:87]
	v_lshl_add_u64 v[4:5], v[38:39], 1, v[4:5]
	s_waitcnt lgkmcnt(0)
	v_cvt_pk_bf16_f32 v0, v0, v2
	v_add_co_u32_e32 v2, vcc, 0x271c0000, v4
	s_nop 1
	v_addc_co_u32_e32 v3, vcc, 0, v5, vcc
	ds_write_b32 v208, v0 offset:1088
.LBB0_714:
	s_or_b64 exec, exec, s[0:1]
	s_mov_b64 s[0:1], 0x1200
	s_waitcnt lgkmcnt(0)
	v_lshl_add_u64 v[2:3], v[92:93], 0, s[0:1]
	flat_load_ushort v0, v[2:3] offset:64
	s_nop 0
	flat_load_dword v2, v[72:73] offset:36
	s_waitcnt vmcnt(0) lgkmcnt(0)
	v_lshlrev_b32_e32 v0, 16, v0
	v_mul_f32_e32 v3, 0x3d372713, v0
	v_mul_f32_e32 v3, v3, v0
	v_fma_f32 v3, v3, v0, v0
	v_mul_f32_e32 v3, 0x3f4c422a, v3
	v_mul_f32_e32 v3, 0xc038aa3b, v3
	v_exp_f32_e32 v3, v3
	v_add_f32_e32 v2, v7, v2
	v_add_f32_e32 v3, 1.0, v3
	v_rcp_f32_e32 v3, v3
	s_nop 0
	v_mul_f32_e32 v0, v3, v0
	v_mul_f32_e32 v0, v2, v0
	s_nop 1
	v_mov_b32_dpp v2, v0 quad_perm:[1,0,3,2] row_mask:0xf bank_mask:0xf
	s_and_saveexec_b64 s[0:1], s[4:5]
	s_cbranch_execz .LBB0_716
	v_lshl_add_u64 v[4:5], v[22:23], 0, s[86:87]
	v_lshl_add_u64 v[4:5], v[38:39], 1, v[4:5]
	s_waitcnt lgkmcnt(0)
	v_cvt_pk_bf16_f32 v0, v0, v2
	v_add_co_u32_e32 v2, vcc, 0x271c0000, v4
	s_nop 1
	v_addc_co_u32_e32 v3, vcc, 0, v5, vcc
	ds_write_b32 v208, v0 offset:1216
; __device__ __forceinline__ float bf2f(unsigned short h) { return __uint_as_float(((unsigned)h) << 16); }
; __device__ __forceinline__ unsigned cvtpk(float lo, float hi) { unsigned r; asm volatile("v_cvt_pk_bf16_f32 %0, %1, %2" : "=v"(r) : "v"(lo), "v"(hi)); return r; }
; __device__ __forceinline__ int crow(int r, int hi) { return (r & 3) + 8 * (r >> 2) + 4 * hi; }
; __device__ __forceinline__ void ph_misc(const Args& a, char* lds, int l) {
;     ...
;         for (int ci = 0; ci < 2; ++ci)
; #pragma unroll
;             for (int r = 0; r < 16; ++r) { const int t = 32 * tb + crow(r, hi), c = 32 * (cb0 + ci) + r32; const size_t row = row0 + t;
;                 const float uval = gelu_tanh(bf2f(P[row * NIN + PC_U + g * 128 + c])); const float val = uval * (acc[ci][r] + b_s[l * 512 + g * 128 + t]);
;                 const float vn = __shfl_xor(val, 1); if ((r32 & 1) == 0) *(unsigned*)(MIX + row * DM + 1024 + g * 128 + c) = cvtpk(val, vn); }
.LBB0_716:
	s_or_b64 exec, exec, s[0:1]
	s_mov_b64 s[0:1], 0x1200
	s_waitcnt lgkmcnt(0)
	v_lshl_add_u64 v[2:3], v[94:95], 0, s[0:1]
	flat_load_ushort v0, v[2:3] offset:64
	s_nop 0
	flat_load_dword v2, v[72:73] offset:40
	s_waitcnt vmcnt(0) lgkmcnt(0)
	v_lshlrev_b32_e32 v0, 16, v0
	v_mul_f32_e32 v3, 0x3d372713, v0
	v_mul_f32_e32 v3, v3, v0
	v_fma_f32 v3, v3, v0, v0
	v_mul_f32_e32 v3, 0x3f4c422a, v3
	v_mul_f32_e32 v3, 0xc038aa3b, v3
	v_exp_f32_e32 v3, v3
	v_add_f32_e32 v2, v8, v2
	v_add_f32_e32 v3, 1.0, v3
	v_rcp_f32_e32 v3, v3
	s_nop 0
	v_mul_f32_e32 v0, v3, v0
	v_mul_f32_e32 v0, v2, v0
	s_nop 1
	v_mov_b32_dpp v2, v0 quad_perm:[1,0,3,2] row_mask:0xf bank_mask:0xf
	s_and_saveexec_b64 s[0:1], s[4:5]
	s_cbranch_execz .LBB0_718
	v_lshl_add_u64 v[4:5], v[96:97], 0, s[86:87]
	v_lshl_add_u64 v[4:5], v[38:39], 1, v[4:5]
	s_waitcnt lgkmcnt(0)
	v_cvt_pk_bf16_f32 v0, v0, v2
	v_add_co_u32_e32 v2, vcc, 0x271c0000, v4
	s_nop 1
	v_addc_co_u32_e32 v3, vcc, 0, v5, vcc
	ds_write_b32 v208, v0 offset:1344
.LBB0_718:
	s_or_b64 exec, exec, s[0:1]
	s_mov_b64 s[0:1], 0x1200
	s_waitcnt lgkmcnt(0)
	v_lshl_add_u64 v[2:3], v[98:99], 0, s[0:1]
	flat_load_ushort v0, v[2:3] offset:64
	s_nop 0
	flat_load_dword v2, v[72:73] offset:44
	s_waitcnt vmcnt(0) lgkmcnt(0)
	v_lshlrev_b32_e32 v0, 16, v0
	v_mul_f32_e32 v3, 0x3d372713, v0
	v_mul_f32_e32 v3, v3, v0
	v_fma_f32 v3, v3, v0, v0
	v_mul_f32_e32 v3, 0x3f4c422a, v3
	v_mul_f32_e32 v3, 0xc038aa3b, v3
	v_exp_f32_e32 v3, v3
	v_add_f32_e32 v2, v9, v2
	v_add_f32_e32 v3, 1.0, v3
	v_rcp_f32_e32 v3, v3
	s_nop 0
	v_mul_f32_e32 v0, v3, v0
	v_mul_f32_e32 v0, v2, v0
	s_nop 1
	v_mov_b32_dpp v2, v0 quad_perm:[1,0,3,2] row_mask:0xf bank_mask:0xf
	s_and_saveexec_b64 s[0:1], s[4:5]
	s_cbranch_execz .LBB0_720
	v_lshl_add_u64 v[4:5], v[24:25], 0, s[86:87]
	v_lshl_add_u64 v[4:5], v[38:39], 1, v[4:5]
	s_waitcnt lgkmcnt(0)
	v_cvt_pk_bf16_f32 v0, v0, v2
	v_add_co_u32_e32 v2, vcc, 0x271c0000, v4
	s_nop 1
	v_addc_co_u32_e32 v3, vcc, 0, v5, vcc
	ds_write_b32 v208, v0 offset:1472
.LBB0_720:
	s_or_b64 exec, exec, s[0:1]
	s_mov_b64 s[0:1], 0x1200
	s_waitcnt lgkmcnt(0)
	v_lshl_add_u64 v[2:3], v[100:101], 0, s[0:1]
	flat_load_ushort v0, v[2:3] offset:64
	s_nop 0
	flat_load_dword v2, v[72:73] offset:64
	s_waitcnt vmcnt(0) lgkmcnt(0)
	v_lshlrev_b32_e32 v0, 16, v0
	v_mul_f32_e32 v3, 0x3d372713, v0
	v_mul_f32_e32 v3, v3, v0
	v_fma_f32 v3, v3, v0, v0
	v_mul_f32_e32 v3, 0x3f4c422a, v3
	v_mul_f32_e32 v3, 0xc038aa3b, v3
	v_exp_f32_e32 v3, v3
	v_add_f32_e32 v2, v10, v2
	v_add_f32_e32 v3, 1.0, v3
	v_rcp_f32_e32 v3, v3
	s_nop 0
	v_mul_f32_e32 v0, v3, v0
	v_mul_f32_e32 v0, v2, v0
	s_nop 1
	v_mov_b32_dpp v2, v0 quad_perm:[1,0,3,2] row_mask:0xf bank_mask:0xf
	s_and_saveexec_b64 s[0:1], s[4:5]
	s_cbranch_execz .LBB0_722
	v_lshl_add_u64 v[4:5], v[102:103], 0, s[86:87]
	v_lshl_add_u64 v[4:5], v[38:39], 1, v[4:5]
	s_waitcnt lgkmcnt(0)
	v_cvt_pk_bf16_f32 v0, v0, v2
	v_add_co_u32_e32 v2, vcc, 0x271c0000, v4
	s_nop 1
	v_addc_co_u32_e32 v3, vcc, 0, v5, vcc
	ds_write_b32 v208, v0 offset:2112
.LBB0_722:
	s_or_b64 exec, exec, s[0:1]
	s_mov_b64 s[0:1], 0x1200
	s_waitcnt lgkmcnt(0)
	v_lshl_add_u64 v[2:3], v[104:105], 0, s[0:1]
	flat_load_ushort v0, v[2:3] offset:64
	s_nop 0
	flat_load_dword v2, v[72:73] offset:68
	s_waitcnt vmcnt(0) lgkmcnt(0)
	v_lshlrev_b32_e32 v0, 16, v0
	v_mul_f32_e32 v3, 0x3d372713, v0
	v_mul_f32_e32 v3, v3, v0
	v_fma_f32 v3, v3, v0, v0
	v_mul_f32_e32 v3, 0x3f4c422a, v3
	v_mul_f32_e32 v3, 0xc038aa3b, v3
	v_exp_f32_e32 v3, v3
	v_add_f32_e32 v2, v11, v2
	v_add_f32_e32 v3, 1.0, v3
	v_rcp_f32_e32 v3, v3
	s_nop 0
	v_mul_f32_e32 v0, v3, v0
	v_mul_f32_e32 v0, v2, v0
	s_nop 1
	v_mov_b32_dpp v2, v0 quad_perm:[1,0,3,2] row_mask:0xf bank_mask:0xf
	s_and_saveexec_b64 s[0:1], s[4:5]
	s_cbranch_execz .LBB0_724
	v_lshl_add_u64 v[4:5], v[26:27], 0, s[86:87]
	v_lshl_add_u64 v[4:5], v[38:39], 1, v[4:5]
	s_waitcnt lgkmcnt(0)
	v_cvt_pk_bf16_f32 v0, v0, v2
	v_add_co_u32_e32 v2, vcc, 0x271c0000, v4
	s_nop 1
	v_addc_co_u32_e32 v3, vcc, 0, v5, vcc
	ds_write_b32 v208, v0 offset:2240
.LBB0_724:
	s_or_b64 exec, exec, s[0:1]
	s_mov_b64 s[0:1], 0x1200
	s_waitcnt lgkmcnt(0)
	v_lshl_add_u64 v[2:3], v[106:107], 0, s[0:1]
	flat_load_ushort v0, v[2:3] offset:64
	s_nop 0
	flat_load_dword v2, v[72:73] offset:72
	s_waitcnt vmcnt(0) lgkmcnt(0)
	v_lshlrev_b32_e32 v0, 16, v0
	v_mul_f32_e32 v3, 0x3d372713, v0
	v_mul_f32_e32 v3, v3, v0
	v_fma_f32 v3, v3, v0, v0
	v_mul_f32_e32 v3, 0x3f4c422a, v3
	v_mul_f32_e32 v3, 0xc038aa3b, v3
	v_exp_f32_e32 v3, v3
	v_add_f32_e32 v2, v12, v2
	v_add_f32_e32 v3, 1.0, v3
	v_rcp_f32_e32 v3, v3
	s_nop 0
	v_mul_f32_e32 v0, v3, v0
	v_mul_f32_e32 v0, v2, v0
	s_nop 1
	v_mov_b32_dpp v2, v0 quad_perm:[1,0,3,2] row_mask:0xf bank_mask:0xf
	s_and_saveexec_b64 s[0:1], s[4:5]
	s_cbranch_execz .LBB0_726
	v_lshl_add_u64 v[4:5], v[108:109], 0, s[86:87]
	v_lshl_add_u64 v[4:5], v[38:39], 1, v[4:5]
	s_waitcnt lgkmcnt(0)
	v_cvt_pk_bf16_f32 v0, v0, v2
	v_add_co_u32_e32 v2, vcc, 0x271c0000, v4
	s_nop 1
	v_addc_co_u32_e32 v3, vcc, 0, v5, vcc
	ds_write_b32 v208, v0 offset:2368
; __device__ __forceinline__ float bf2f(unsigned short h) { return __uint_as_float(((unsigned)h) << 16); }
; __device__ __forceinline__ unsigned cvtpk(float lo, float hi) { unsigned r; asm volatile("v_cvt_pk_bf16_f32 %0, %1, %2" : "=v"(r) : "v"(lo), "v"(hi)); return r; }
; __device__ __forceinline__ int crow(int r, int hi) { return (r & 3) + 8 * (r >> 2) + 4 * hi; }
; __device__ __forceinline__ void ph_misc(const Args& a, char* lds, int l) {
;     ...
;         for (int ci = 0; ci < 2; ++ci)
; #pragma unroll
;             for (int r = 0; r < 16; ++r) { const int t = 32 * tb + crow(r, hi), c = 32 * (cb0 + ci) + r32; const size_t row = row0 + t;
;                 const float uval = gelu_tanh(bf2f(P[row * NIN + PC_U + g * 128 + c])); const float val = uval * (acc[ci][r] + b_s[l * 512 + g * 128 + t]);
;                 const float vn = __shfl_xor(val, 1); if ((r32 & 1) == 0) *(unsigned*)(MIX + row * DM + 1024 + g * 128 + c) = cvtpk(val, vn); }
.LBB0_726:
	s_or_b64 exec, exec, s[0:1]
	s_mov_b64 s[0:1], 0x1200
	s_waitcnt lgkmcnt(0)
	v_lshl_add_u64 v[2:3], v[110:111], 0, s[0:1]
	flat_load_ushort v0, v[2:3] offset:64
	s_nop 0
	flat_load_dword v2, v[72:73] offset:76
	s_waitcnt vmcnt(0) lgkmcnt(0)
	v_lshlrev_b32_e32 v0, 16, v0
	v_mul_f32_e32 v3, 0x3d372713, v0
	v_mul_f32_e32 v3, v3, v0
	v_fma_f32 v3, v3, v0, v0
	v_mul_f32_e32 v3, 0x3f4c422a, v3
	v_mul_f32_e32 v3, 0xc038aa3b, v3
	v_exp_f32_e32 v3, v3
	v_add_f32_e32 v2, v13, v2
	v_add_f32_e32 v3, 1.0, v3
	v_rcp_f32_e32 v3, v3
	s_nop 0
	v_mul_f32_e32 v0, v3, v0
	v_mul_f32_e32 v0, v2, v0
	s_nop 1
	v_mov_b32_dpp v2, v0 quad_perm:[1,0,3,2] row_mask:0xf bank_mask:0xf
	s_and_saveexec_b64 s[0:1], s[4:5]
	s_cbranch_execz .LBB0_728
	v_lshl_add_u64 v[4:5], v[28:29], 0, s[86:87]
	v_lshl_add_u64 v[4:5], v[38:39], 1, v[4:5]
	s_waitcnt lgkmcnt(0)
	v_cvt_pk_bf16_f32 v0, v0, v2
	v_add_co_u32_e32 v2, vcc, 0x271c0000, v4
	s_nop 1
	v_addc_co_u32_e32 v3, vcc, 0, v5, vcc
	ds_write_b32 v208, v0 offset:2496
.LBB0_728:
	s_or_b64 exec, exec, s[0:1]
	s_mov_b64 s[0:1], 0x1200
	s_waitcnt lgkmcnt(0)
	v_lshl_add_u64 v[2:3], v[112:113], 0, s[0:1]
	flat_load_ushort v0, v[2:3] offset:64
	s_nop 0
	flat_load_dword v2, v[72:73] offset:96
	s_waitcnt vmcnt(0) lgkmcnt(0)
	v_lshlrev_b32_e32 v0, 16, v0
	v_mul_f32_e32 v3, 0x3d372713, v0
	v_mul_f32_e32 v3, v3, v0
	v_fma_f32 v3, v3, v0, v0
	v_mul_f32_e32 v3, 0x3f4c422a, v3
	v_mul_f32_e32 v3, 0xc038aa3b, v3
	v_exp_f32_e32 v3, v3
	v_add_f32_e32 v2, v14, v2
	v_add_f32_e32 v3, 1.0, v3
	v_rcp_f32_e32 v3, v3
	s_nop 0
	v_mul_f32_e32 v0, v3, v0
	v_mul_f32_e32 v0, v2, v0
	s_nop 1
	v_mov_b32_dpp v2, v0 quad_perm:[1,0,3,2] row_mask:0xf bank_mask:0xf
	s_and_saveexec_b64 s[0:1], s[4:5]
	s_cbranch_execz .LBB0_730
	v_lshl_add_u64 v[4:5], v[114:115], 0, s[86:87]
	v_lshl_add_u64 v[4:5], v[38:39], 1, v[4:5]
	s_waitcnt lgkmcnt(0)
	v_cvt_pk_bf16_f32 v0, v0, v2
	v_add_co_u32_e32 v2, vcc, 0x271c0000, v4
	s_nop 1
	v_addc_co_u32_e32 v3, vcc, 0, v5, vcc
	ds_write_b32 v208, v0 offset:3136
.LBB0_730:
	s_or_b64 exec, exec, s[0:1]
	s_mov_b64 s[0:1], 0x1200
	s_waitcnt lgkmcnt(0)
	v_lshl_add_u64 v[2:3], v[116:117], 0, s[0:1]
	flat_load_ushort v0, v[2:3] offset:64
	s_nop 0
	flat_load_dword v2, v[72:73] offset:100
	s_waitcnt vmcnt(0) lgkmcnt(0)
	v_lshlrev_b32_e32 v0, 16, v0
	v_mul_f32_e32 v3, 0x3d372713, v0
	v_mul_f32_e32 v3, v3, v0
	v_fma_f32 v3, v3, v0, v0
	v_mul_f32_e32 v3, 0x3f4c422a, v3
	v_mul_f32_e32 v3, 0xc038aa3b, v3
	v_exp_f32_e32 v3, v3
	v_add_f32_e32 v2, v15, v2
	v_add_f32_e32 v3, 1.0, v3
	v_rcp_f32_e32 v3, v3
	s_nop 0
	v_mul_f32_e32 v0, v3, v0
	v_mul_f32_e32 v0, v2, v0
	s_nop 1
	v_mov_b32_dpp v2, v0 quad_perm:[1,0,3,2] row_mask:0xf bank_mask:0xf
	s_and_saveexec_b64 s[0:1], s[4:5]
	s_cbranch_execz .LBB0_732
	v_lshl_add_u64 v[4:5], v[30:31], 0, s[86:87]
	v_lshl_add_u64 v[4:5], v[38:39], 1, v[4:5]
	s_waitcnt lgkmcnt(0)
	v_cvt_pk_bf16_f32 v0, v0, v2
	v_add_co_u32_e32 v2, vcc, 0x271c0000, v4
	s_nop 1
	v_addc_co_u32_e32 v3, vcc, 0, v5, vcc
	ds_write_b32 v208, v0 offset:3264
.LBB0_732:
	s_or_b64 exec, exec, s[0:1]
	s_mov_b64 s[0:1], 0x1200
	s_waitcnt lgkmcnt(0)
	v_lshl_add_u64 v[2:3], v[118:119], 0, s[0:1]
	flat_load_ushort v0, v[2:3] offset:64
	s_nop 0
	flat_load_dword v2, v[72:73] offset:104
	s_waitcnt vmcnt(0) lgkmcnt(0)
	v_lshlrev_b32_e32 v0, 16, v0
	v_mul_f32_e32 v3, 0x3d372713, v0
	v_mul_f32_e32 v3, v3, v0
	v_fma_f32 v3, v3, v0, v0
	v_mul_f32_e32 v3, 0x3f4c422a, v3
	v_mul_f32_e32 v3, 0xc038aa3b, v3
	v_exp_f32_e32 v3, v3
	v_add_f32_e32 v2, v16, v2
	v_add_f32_e32 v3, 1.0, v3
	v_rcp_f32_e32 v3, v3
	s_nop 0
	v_mul_f32_e32 v0, v3, v0
	v_mul_f32_e32 v0, v2, v0
	s_nop 1
	v_mov_b32_dpp v2, v0 quad_perm:[1,0,3,2] row_mask:0xf bank_mask:0xf
	s_and_saveexec_b64 s[0:1], s[4:5]
	s_cbranch_execz .LBB0_734
	v_lshl_add_u64 v[4:5], v[120:121], 0, s[86:87]
	v_lshl_add_u64 v[4:5], v[38:39], 1, v[4:5]
	s_waitcnt lgkmcnt(0)
	v_cvt_pk_bf16_f32 v0, v0, v2
	v_add_co_u32_e32 v2, vcc, 0x271c0000, v4
	s_nop 1
	v_addc_co_u32_e32 v3, vcc, 0, v5, vcc
	ds_write_b32 v208, v0 offset:3392
.LBB0_734:
	s_or_b64 exec, exec, s[0:1]
	s_mov_b64 s[0:1], 0x1200
	s_waitcnt lgkmcnt(0)
	v_lshl_add_u64 v[2:3], v[122:123], 0, s[0:1]
	flat_load_ushort v0, v[2:3] offset:64
	s_nop 0
	flat_load_dword v2, v[72:73] offset:108
	s_waitcnt vmcnt(0) lgkmcnt(0)
	v_lshlrev_b32_e32 v0, 16, v0
	v_mul_f32_e32 v3, 0x3d372713, v0
	v_mul_f32_e32 v3, v3, v0
	v_fma_f32 v3, v3, v0, v0
	v_mul_f32_e32 v3, 0x3f4c422a, v3
	v_mul_f32_e32 v3, 0xc038aa3b, v3
	v_exp_f32_e32 v3, v3
	v_add_f32_e32 v2, v17, v2
	v_add_f32_e32 v3, 1.0, v3
	v_rcp_f32_e32 v3, v3
	s_nop 0
	v_mul_f32_e32 v0, v3, v0
	v_mul_f32_e32 v0, v2, v0
	s_nop 1
	v_mov_b32_dpp v2, v0 quad_perm:[1,0,3,2] row_mask:0xf bank_mask:0xf
	s_and_saveexec_b64 s[0:1], s[4:5]
	s_cbranch_execz .LBB0_659
	v_lshl_add_u64 v[4:5], v[32:33], 0, s[86:87]
	v_lshl_add_u64 v[4:5], v[38:39], 1, v[4:5]
	s_waitcnt lgkmcnt(0)
	v_cvt_pk_bf16_f32 v0, v0, v2
	v_add_co_u32_e32 v2, vcc, 0x271c0000, v4
	s_nop 1
	v_addc_co_u32_e32 v3, vcc, 0, v5, vcc
	ds_write_b32 v208, v0 offset:3520
	s_branch .LBB0_659
